# merge row loop: next-row cg/s loads no longer waited in the loop header (converted after the main loads are issued)
# baseline (speedup 1.0000x reference)
.LBB0_621:
	v_lshl_add_u64 v[46:47], s[14:15], 0, v[70:71]
	v_add_co_u32_e32 v40, vcc, 0x2ec00000, v46
	s_cmp_lg_u32 s101, 0
	s_cbranch_scc1 .Lmg_w2
	s_waitcnt vmcnt(0)
	s_branch .Lmg_w
.Lmg_w2:
	s_waitcnt vmcnt(2)
.Lmg_w:
	v_mov_b32_e32 v210, v36
	v_addc_co_u32_e32 v41, vcc, 0, v47, vcc
	v_add_co_u32_e32 v48, vcc, 0x32e00000, v46
	global_load_dwordx4 v[40:43], v[40:41], off
	s_nop 0
	v_addc_co_u32_e32 v49, vcc, 0, v47, vcc
	global_load_dwordx4 v[48:51], v[48:49], off
	v_add_co_u32_e32 v82, vcc, 0x26800000, v44
	s_mov_b32 s4, 0xf800000
	s_nop 0
	v_addc_co_u32_e32 v83, vcc, 0, v45, vcc
	global_load_dwordx2 v[84:85], v[82:83], off
	v_add_co_u32_e32 v44, vcc, 0x28900000, v44
	v_lshl_add_u64 v[64:65], v[64:65], 0, s[10:11]
	s_nop 0
	v_addc_co_u32_e32 v45, vcc, 0, v45, vcc
	global_load_dwordx2 v[88:89], v[44:45], off
	v_add_co_u32_e32 v44, vcc, 0x37000000, v46
	v_lshl_add_u64 v[72:73], v[72:73], 0, s[10:11]
	s_nop 0
	v_addc_co_u32_e32 v45, vcc, 0, v47, vcc
	global_load_dwordx4 v[44:47], v[44:45], off
	s_cmp_lg_u32 s101, 0
	s_cbranch_scc0 .Lmg_nc
	s_waitcnt vmcnt(5)
	v_lshlrev_b32_e32 v248, 16, v214
	v_and_b32_e32 v249, 0xffff0000, v214
	v_lshlrev_b32_e32 v250, 16, v215
	v_and_b32_e32 v251, 0xffff0000, v215
	v_lshlrev_b32_e32 v246, 16, v216
	v_and_b32_e32 v247, 0xffff0000, v216
	v_lshlrev_b32_e32 v216, 16, v217
	v_and_b32_e32 v217, 0xffff0000, v217
	v_pk_mul_f32 v[74:75], v[250:251], v[216:217]
	v_pk_mul_f32 v[76:77], v[248:249], v[246:247]
	v_mov_b32_e32 v81, v74
	v_mov_b32_e32 v79, v76
.Lmg_nc:
	s_waitcnt vmcnt(4)
	v_mov_b32_e32 v212, v40
	s_waitcnt vmcnt(3)
	v_lshlrev_b32_e32 v0, 16, v48
	v_mul_f32_e32 v90, v32, v0
	v_lshlrev_b32_e32 v0, 16, v49
	v_mul_f32_e32 v92, v33, v0
	v_lshlrev_b32_e32 v0, 16, v50
	v_mul_f32_e32 v86, v34, v0
	v_lshlrev_b32_e32 v0, 16, v51
	s_waitcnt vmcnt(2)
	v_lshlrev_b32_e32 v95, 16, v84
	v_mul_f32_e32 v82, v35, v0
	v_mul_f32_e32 v0, 0x3d372713, v95
	v_mul_f32_e32 v0, v0, v95
	v_mov_b32_e32 v78, v95
	v_fmac_f32_e32 v78, v0, v78
	v_mul_f32_e32 v0, 0x3f4c422a, v78
	v_add_f32_e32 v0, v0, v0
	v_mul_f32_e32 v0, 0x3fb8aa3b, v0
	v_exp_f32_e32 v0, v0
	v_and_b32_e32 v94, 0xffff0000, v48
	v_pk_mul_f32 v[94:95], v[210:211], v[94:95]
	v_mov_b32_e32 v78, v2
	v_add_f32_e32 v0, 1.0, v0
	v_rcp_f32_e32 v0, v0
	v_pk_mov_b32 v[48:49], v[48:49], v[84:85] op_sel:[1,0]
	s_waitcnt vmcnt(1)
	v_lshlrev_b32_e32 v76, 16, v88
	v_and_b32_e32 v49, 0xffff0000, v49
	v_fma_f32 v91, v0, -2.0, 1.0
	v_pk_add_f32 v[90:91], v[212:213], v[90:91]
	v_and_b32_e32 v48, 0xffff0000, v48
	v_mul_f32_e32 v0, v95, v91
	v_add_f32_e32 v40, v94, v90
	v_pk_mul_f32 v[90:91], v[52:53], v[78:79]
	v_mul_f32_e32 v0, v40, v0
	v_fma_f32 v40, v4, v60, v90
	v_add_f32_e32 v40, v40, v91
	v_add_f32_e32 v40, v12, v40
	v_mul_f32_e32 v60, v40, v76
	v_mul_f32_e32 v40, 0x3d372713, v49
	v_mul_f32_e32 v40, v40, v49
	v_mov_b32_e32 v76, v49
	v_fmac_f32_e32 v76, v40, v76
	v_mul_f32_e32 v40, 0x3f4c422a, v76
	v_add_f32_e32 v40, v40, v40
	v_mul_f32_e32 v40, 0x3fb8aa3b, v40
	v_exp_f32_e32 v40, v40
	v_mov_b32_e32 v210, v37
	v_mov_b32_e32 v212, v41
	v_pk_mul_f32 v[48:49], v[210:211], v[48:49]
	v_add_f32_e32 v40, 1.0, v40
	v_rcp_f32_e32 v40, v40
	v_mov_b32_e32 v76, v3
	v_and_b32_e32 v80, 0xffff0000, v88
	v_mov_b32_e32 v210, v38
	v_fma_f32 v93, v40, -2.0, 1.0
	v_pk_add_f32 v[40:41], v[212:213], v[92:93]
	v_mov_b32_e32 v212, v42
	v_mul_f32_e32 v41, v49, v41
	v_add_f32_e32 v40, v48, v40
	v_mul_f32_e32 v48, v40, v41
	v_pk_mul_f32 v[40:41], v[8:9], v[76:77]
	v_lshlrev_b32_e32 v74, 16, v89
	v_fma_f32 v40, v5, v61, v40
	v_add_f32_e32 v40, v40, v41
	v_add_f32_e32 v40, v13, v40
	v_lshlrev_b32_e32 v41, 16, v85
	v_mul_f32_e32 v49, v40, v80
	v_and_b32_e32 v40, 0xffff0000, v50
	v_mul_f32_e32 v50, 0x3d372713, v41
	v_mul_f32_e32 v50, v50, v41
	v_mov_b32_e32 v61, v41
	v_fmac_f32_e32 v61, v50, v61
	v_mul_f32_e32 v50, 0x3f4c422a, v61
	v_add_f32_e32 v50, v50, v50
	v_mul_f32_e32 v50, 0x3fb8aa3b, v50
	v_exp_f32_e32 v50, v50
	v_pk_mul_f32 v[40:41], v[210:211], v[40:41]
	v_mov_b32_e32 v80, v56
	v_mov_b32_e32 v210, v39
	v_add_f32_e32 v50, 1.0, v50
	v_rcp_f32_e32 v50, v50
	v_and_b32_e32 v88, 0xffff0000, v89
	v_mul_f32_e32 v76, v0, v0
	v_fmac_f32_e32 v76, v48, v48
	v_fma_f32 v87, v50, -2.0, 1.0
	v_pk_add_f32 v[86:87], v[212:213], v[86:87]
	v_mov_b32_e32 v212, v43
	v_mul_f32_e32 v41, v41, v87
	v_add_f32_e32 v40, v40, v86
	v_mul_f32_e32 v50, v40, v41
	v_pk_mul_f32 v[40:41], v[54:55], v[80:81]
	v_fmac_f32_e32 v76, v50, v50
	v_fma_f32 v40, v6, v58, v40
	v_add_f32_e32 v40, v40, v41
	v_and_b32_e32 v41, 0xffff0000, v85
	v_add_f32_e32 v40, v14, v40
	v_mul_f32_e32 v42, 0x3d372713, v41
	v_mul_f32_e32 v58, v40, v74
	v_and_b32_e32 v40, 0xffff0000, v51
	v_mul_f32_e32 v42, v42, v41
	v_mov_b32_e32 v51, v41
	v_fmac_f32_e32 v51, v42, v51
	v_mul_f32_e32 v42, 0x3f4c422a, v51
	v_add_f32_e32 v42, v42, v42
	v_mul_f32_e32 v42, 0x3fb8aa3b, v42
	v_exp_f32_e32 v42, v42
	v_pk_mul_f32 v[40:41], v[210:211], v[40:41]
	v_mov_b32_e32 v74, v57
	v_add_f32_e32 v42, 1.0, v42
	v_rcp_f32_e32 v42, v42
	s_nop 0
	v_fma_f32 v83, v42, -2.0, 1.0
	v_pk_add_f32 v[42:43], v[212:213], v[82:83]
	s_nop 0
	v_mul_f32_e32 v41, v41, v43
	v_add_f32_e32 v40, v40, v42
	v_mul_f32_e32 v51, v40, v41
	v_pk_mul_f32 v[40:41], v[10:11], v[74:75]
	s_waitcnt vmcnt(0)
	v_lshlrev_b32_e32 v42, 16, v45
	v_fma_f32 v40, v7, v59, v40
	v_add_f32_e32 v40, v40, v41
	v_add_f32_e32 v40, v15, v40
	v_and_b32_e32 v41, 0xffff0000, v44
	v_mul_f32_e32 v59, v40, v88
	v_lshlrev_b32_e32 v40, 16, v44
	v_mul_f32_e32 v61, v41, v41
	v_fmac_f32_e32 v61, v40, v40
	v_and_b32_e32 v43, 0xffff0000, v45
	v_fmac_f32_e32 v61, v42, v42
	v_lshlrev_b32_e32 v44, 16, v46
	v_fmac_f32_e32 v61, v43, v43
	v_and_b32_e32 v45, 0xffff0000, v46
	v_fmac_f32_e32 v61, v44, v44
	v_lshlrev_b32_e32 v46, 16, v47
	v_fmac_f32_e32 v61, v45, v45
	v_and_b32_e32 v47, 0xffff0000, v47
	v_fmac_f32_e32 v61, v46, v46
	v_fmac_f32_e32 v61, v47, v47
	v_fmac_f32_e32 v76, v51, v51
	v_mul_f32_e32 v74, v49, v49
	v_add_f32_dpp v61, v61, v61 quad_perm:[1,0,3,2] row_mask:0xf bank_mask:0xf bound_ctrl:1
	v_add_f32_dpp v76, v76, v76 quad_perm:[1,0,3,2] row_mask:0xf bank_mask:0xf bound_ctrl:1
	v_fmac_f32_e32 v74, v60, v60
	v_add_f32_dpp v61, v61, v61 quad_perm:[2,3,0,1] row_mask:0xf bank_mask:0xf bound_ctrl:1
	v_add_f32_dpp v76, v76, v76 quad_perm:[2,3,0,1] row_mask:0xf bank_mask:0xf bound_ctrl:1
	v_fmac_f32_e32 v74, v58, v58
	v_add_f32_dpp v61, v61, v61 row_half_mirror row_mask:0xf bank_mask:0xf bound_ctrl:1
	v_add_f32_dpp v76, v76, v76 row_half_mirror row_mask:0xf bank_mask:0xf bound_ctrl:1
	v_fmac_f32_e32 v74, v59, v59
	v_add_f32_dpp v61, v61, v61 row_mirror row_mask:0xf bank_mask:0xf bound_ctrl:1
	v_mov_b32_e32 v78, v61
	s_nop 1
	v_permlane16_swap_b32_e32 v61, v78
	v_add_f32_e32 v61, v61, v78
	v_mov_b32_e32 v78, v61
	s_nop 1
	v_permlane32_swap_b32_e32 v61, v78
	v_add_f32_dpp v76, v76, v76 row_mirror row_mask:0xf bank_mask:0xf bound_ctrl:1
	v_add_f32_e32 v61, v61, v78
	v_mov_b32_e32 v78, v76
	s_nop 1
	v_permlane16_swap_b32_e32 v76, v78
	v_add_f32_dpp v74, v74, v74 quad_perm:[1,0,3,2] row_mask:0xf bank_mask:0xf bound_ctrl:1
	v_add_f32_e32 v76, v76, v78
	v_mov_b32_e32 v78, v76
	v_add_f32_dpp v74, v74, v74 quad_perm:[2,3,0,1] row_mask:0xf bank_mask:0xf bound_ctrl:1
	s_nop 0
	v_permlane32_swap_b32_e32 v76, v78
	v_add_f32_dpp v74, v74, v74 row_half_mirror row_mask:0xf bank_mask:0xf bound_ctrl:1
	v_add_f32_e32 v76, v76, v78
	v_fmamk_f32 v61, v61, 0x3b000000, v236
	v_add_f32_dpp v74, v74, v74 row_mirror row_mask:0xf bank_mask:0xf bound_ctrl:1
	v_mov_b32_e32 v78, v74
	s_nop 1
	v_permlane16_swap_b32_e32 v74, v78
	v_add_f32_e32 v74, v74, v78
	v_mov_b32_e32 v78, v74
	s_nop 1
	v_permlane32_swap_b32_e32 v74, v78
	v_add_f32_e32 v74, v74, v78
	v_cmp_gt_f32_e32 vcc, s4, v61
	v_mul_f32_e32 v78, 0x4f800000, v61
	v_fmamk_f32 v76, v76, 0x3b800000, v236
	v_cndmask_b32_e32 v61, v61, v78, vcc
	v_sqrt_f32_e32 v78, v61
	v_fmamk_f32 v74, v74, 0x3b800000, v236
	v_add_u32_e32 v80, -1, v78
	v_fma_f32 v82, -v80, v78, v61
	v_cmp_ge_f32_e64 s[0:1], 0, v82
	v_add_u32_e32 v82, 1, v78
	s_nop 0
	v_cndmask_b32_e64 v80, v78, v80, s[0:1]
	v_fma_f32 v78, -v82, v78, v61
	v_cmp_lt_f32_e64 s[0:1], 0, v78
	s_nop 1
	v_cndmask_b32_e64 v78, v80, v82, s[0:1]
	v_mul_f32_e32 v80, 0x37800000, v78
	v_cndmask_b32_e32 v78, v78, v80, vcc
	v_cmp_class_f32_e32 vcc, v61, v238
	s_nop 1
	v_cndmask_b32_e32 v61, v78, v61, vcc
	v_div_scale_f32 v78, s[0:1], v61, v61, 1.0
	v_rcp_f32_e32 v80, v78
	s_nop 0
	v_fma_f32 v82, -v78, v80, 1.0
	v_fmac_f32_e32 v80, v82, v80
	v_div_scale_f32 v82, vcc, 1.0, v61, 1.0
	v_mul_f32_e32 v83, v82, v80
	v_fma_f32 v84, -v78, v83, v82
	v_fmac_f32_e32 v83, v84, v80
	v_fma_f32 v78, -v78, v83, v82
	v_div_fmas_f32 v78, v78, v80, v83
	v_div_fixup_f32 v61, v78, v61, 1.0
	v_cmp_gt_f32_e32 vcc, s4, v76
	v_mul_f32_e32 v78, 0x4f800000, v76
	v_mul_f32_e32 v40, v61, v40
	v_cndmask_b32_e32 v76, v76, v78, vcc
	v_sqrt_f32_e32 v78, v76
	v_mul_f32_e32 v41, v61, v41
	v_mul_f32_e32 v40, v20, v40
	v_mul_f32_e32 v41, v21, v41
	v_add_u32_e32 v80, -1, v78
	v_fma_f32 v82, -v80, v78, v76
	v_cmp_ge_f32_e64 s[0:1], 0, v82
	v_add_u32_e32 v82, 1, v78
	v_cvt_pk_bf16_f32 v40, v40, v41
	v_mul_f32_e32 v41, v61, v42
	v_cndmask_b32_e64 v80, v78, v80, s[0:1]
	v_fma_f32 v78, -v82, v78, v76
	v_cmp_lt_f32_e64 s[0:1], 0, v78
	v_mul_f32_e32 v42, v61, v43
	v_mul_f32_e32 v41, v22, v41
	v_cndmask_b32_e64 v78, v80, v82, s[0:1]
	v_mul_f32_e32 v80, 0x37800000, v78
	v_cndmask_b32_e32 v78, v78, v80, vcc
	v_cmp_class_f32_e32 vcc, v76, v238
	v_mul_f32_e32 v42, v23, v42
	v_cvt_pk_bf16_f32 v41, v41, v42
	v_mul_f32_e32 v42, v61, v44
	v_cndmask_b32_e32 v76, v78, v76, vcc
	v_div_scale_f32 v78, s[0:1], v76, v76, 1.0
	v_rcp_f32_e32 v80, v78
	v_mul_f32_e32 v43, v61, v45
	v_mul_f32_e32 v42, v16, v42
	v_mul_f32_e32 v43, v17, v43
	v_fma_f32 v82, -v78, v80, 1.0
	v_fmac_f32_e32 v80, v82, v80
	v_div_scale_f32 v82, vcc, 1.0, v76, 1.0
	v_mul_f32_e32 v83, v82, v80
	v_fma_f32 v84, -v78, v83, v82
	v_fmac_f32_e32 v83, v84, v80
	v_fma_f32 v78, -v78, v83, v82
	v_div_fmas_f32 v78, v78, v80, v83
	v_div_fixup_f32 v76, v78, v76, 1.0
	v_cmp_gt_f32_e32 vcc, s4, v74
	v_mul_f32_e32 v78, 0x4f800000, v74
	v_cvt_pk_bf16_f32 v42, v42, v43
	v_mul_f32_e32 v43, v61, v46
	v_cndmask_b32_e32 v74, v74, v78, vcc
	v_sqrt_f32_e32 v78, v74
	v_mul_f32_e32 v44, v61, v47
	v_mul_f32_e32 v43, v18, v43
	v_mul_f32_e32 v44, v19, v44
	v_add_u32_e32 v80, -1, v78
	v_fma_f32 v82, -v80, v78, v74
	v_cmp_ge_f32_e64 s[0:1], 0, v82
	v_add_u32_e32 v82, 1, v78
	v_cvt_pk_bf16_f32 v43, v43, v44
	v_lshl_add_u64 v[44:45], s[14:15], 0, v[68:69]
	v_cndmask_b32_e64 v80, v78, v80, s[0:1]
	v_fma_f32 v78, -v82, v78, v74
	v_cmp_lt_f32_e64 s[0:1], 0, v78
	global_store_dwordx4 v[44:45], v[40:43], off
	v_mul_f32_e32 v0, v0, v76
	v_cndmask_b32_e64 v78, v80, v82, s[0:1]
	v_mul_f32_e32 v80, 0x37800000, v78
	v_cndmask_b32_e32 v78, v78, v80, vcc
	v_cmp_class_f32_e32 vcc, v74, v238
	v_mul_f32_e32 v40, v48, v76
	v_mul_f32_e32 v0, v24, v0
	v_cndmask_b32_e32 v74, v78, v74, vcc
	v_div_scale_f32 v78, s[0:1], v74, v74, 1.0
	v_rcp_f32_e32 v80, v78
	v_mul_f32_e32 v40, v25, v40
	v_lshl_add_u64 v[42:43], s[14:15], 0, v[66:67]
	s_mov_b32 s0, 0x16000000
	v_fma_f32 v82, -v78, v80, 1.0
	v_fmac_f32_e32 v80, v82, v80
	v_div_scale_f32 v82, vcc, 1.0, v74, 1.0
	v_mul_f32_e32 v83, v82, v80
	v_fma_f32 v84, -v78, v83, v82
	v_fmac_f32_e32 v83, v84, v80
	v_fma_f32 v78, -v78, v83, v82
	v_div_fmas_f32 v78, v78, v80, v83
	v_cvt_pk_bf16_f32 v40, v0, v40
	v_mul_f32_e32 v0, v50, v76
	v_mul_f32_e32 v41, v51, v76
	v_add_co_u32_e32 v42, vcc, s0, v42
	v_div_fixup_f32 v74, v78, v74, 1.0
	v_mul_f32_e32 v0, v26, v0
	v_mul_f32_e32 v41, v27, v41
	v_addc_co_u32_e32 v43, vcc, 0, v43, vcc
	v_cvt_pk_bf16_f32 v41, v0, v41
	global_store_dwordx2 v[42:43], v[40:41], off offset:1024
	v_mul_f32_e32 v0, v60, v74
	v_mul_f32_e32 v40, v49, v74
	s_mov_b64 s[0:1], 0x800
	v_mul_f32_e32 v0, v28, v0
	v_mul_f32_e32 v40, v29, v40
	v_mul_f32_e32 v41, v59, v74
	s_add_i32 s4, s3, 1
	s_add_i32 s3, s3, 0x10001
	v_lshl_add_u64 v[66:67], v[66:67], 0, s[0:1]
	v_lshl_add_u64 v[68:69], v[68:69], 0, s[0:1]
	s_mov_b64 s[0:1], 0x400
	v_cvt_pk_bf16_f32 v40, v0, v40
	v_mul_f32_e32 v0, v58, v74
	v_mul_f32_e32 v41, v31, v41
	v_lshl_add_u64 v[70:71], v[70:71], 0, s[0:1]
	s_cmp_lt_i32 s3, s8
	s_mov_b32 s3, s4
	v_mov_b32_e32 v60, v2
	v_mov_b32_e32 v61, v3
	v_mov_b32_e32 v58, v56
	v_mov_b32_e32 v59, v57
	v_mov_b32_e32 v2, v79
	v_mov_b32_e32 v3, v77
	v_mov_b32_e32 v56, v81
	v_mov_b32_e32 v57, v75
	v_mul_f32_e32 v0, v30, v0
	v_cvt_pk_bf16_f32 v41, v0, v41
	global_store_dwordx2 v[42:43], v[40:41], off offset:1536
	s_cbranch_scc0 .LBB0_632

.LBB0_626:
	s_mov_b32 s101, 0
	s_add_i32 s0, s4, 1
	v_mov_b32_e32 v79, 0
	s_cmp_eq_u32 s0, s5
	v_mov_b32_e32 v77, 0
	v_mov_b32_e32 v81, 0
	v_mov_b32_e32 v75, 0
	s_cbranch_scc1 .LBB0_621
	v_lshl_add_u64 v[246:247], s[14:15], 0, v[72:73]
	v_add_co_u32_e32 v214, vcc, 0x2aa00000, v246
	s_nop 1
	v_addc_co_u32_e32 v215, vcc, 0, v247, vcc
	v_add_co_u32_e32 v246, vcc, 0x2cb00000, v246
	global_load_dwordx2 v[214:215], v[214:215], off
	s_nop 0
	v_addc_co_u32_e32 v247, vcc, 0, v247, vcc
	global_load_dwordx2 v[216:217], v[246:247], off
	s_mov_b32 s101, 1
	s_branch .LBB0_621

	.amdhsa_kernel _Z14fwd_megakernel6Params
		.amdhsa_group_segment_fixed_size 0
		.amdhsa_private_segment_fixed_size 0
		.amdhsa_kernarg_size 464
		.amdhsa_user_sgpr_count 2
		.amdhsa_user_sgpr_dispatch_ptr 0
		.amdhsa_user_sgpr_queue_ptr 0
		.amdhsa_user_sgpr_kernarg_segment_ptr 1
		.amdhsa_user_sgpr_dispatch_id 0
		.amdhsa_user_sgpr_kernarg_preload_length 0
		.amdhsa_user_sgpr_kernarg_preload_offset 0
		.amdhsa_user_sgpr_private_segment_size 0
		.amdhsa_uses_dynamic_stack 0
		.amdhsa_enable_private_segment 0
		.amdhsa_system_sgpr_workgroup_id_x 1
		.amdhsa_system_sgpr_workgroup_id_y 0
		.amdhsa_system_sgpr_workgroup_id_z 0
		.amdhsa_system_sgpr_workgroup_info 0
		.amdhsa_system_vgpr_workitem_id 2
		.amdhsa_next_free_vgpr 256
		.amdhsa_next_free_sgpr 102
		.amdhsa_accum_offset 256
		.amdhsa_reserve_vcc 1
		.amdhsa_float_round_mode_32 0
		.amdhsa_float_round_mode_16_64 0
		.amdhsa_float_denorm_mode_32 3
		.amdhsa_float_denorm_mode_16_64 3
		.amdhsa_dx10_clamp 1
		.amdhsa_ieee_mode 1
		.amdhsa_fp16_overflow 0
		.amdhsa_tg_split 0
		.amdhsa_exception_fp_ieee_invalid_op 0
		.amdhsa_exception_fp_denorm_src 0
		.amdhsa_exception_fp_ieee_div_zero 0
		.amdhsa_exception_fp_ieee_overflow 0
		.amdhsa_exception_fp_ieee_underflow 0
		.amdhsa_exception_fp_ieee_inexact 0
		.amdhsa_exception_int_div_zero 0
	.end_amdhsa_kernel

amdhsa.kernels:
  - .agpr_count:     0
    .args:
      - .offset:         0
        .size:           208
        .value_kind:     by_value
      - .offset:         208
        .size:           4
        .value_kind:     hidden_block_count_x
      - .offset:         212
        .size:           4
        .value_kind:     hidden_block_count_y
      - .offset:         216
        .size:           4
        .value_kind:     hidden_block_count_z
      - .offset:         220
        .size:           2
        .value_kind:     hidden_group_size_x
      - .offset:         222
        .size:           2
        .value_kind:     hidden_group_size_y
      - .offset:         224
        .size:           2
        .value_kind:     hidden_group_size_z
      - .offset:         226
        .size:           2
        .value_kind:     hidden_remainder_x
      - .offset:         228
        .size:           2
        .value_kind:     hidden_remainder_y
      - .offset:         230
        .size:           2
        .value_kind:     hidden_remainder_z
      - .offset:         248
        .size:           8
        .value_kind:     hidden_global_offset_x
      - .offset:         256
        .size:           8
        .value_kind:     hidden_global_offset_y
      - .offset:         264
        .size:           8
        .value_kind:     hidden_global_offset_z
      - .offset:         272
        .size:           2
        .value_kind:     hidden_grid_dims
      - .offset:         296
        .size:           8
        .value_kind:     hidden_multigrid_sync_arg
      - .offset:         328
        .size:           4
        .value_kind:     hidden_dynamic_lds_size
    .group_segment_fixed_size: 0
    .kernarg_segment_align: 8
    .kernarg_segment_size: 464
    .language:       OpenCL C
    .language_version:
      - 2
      - 0
    .max_flat_workgroup_size: 512
    .name:           _Z14fwd_megakernel6Params
    .private_segment_fixed_size: 0
    .sgpr_count:     108
    .sgpr_spill_count: 182
    .symbol:         _Z14fwd_megakernel6Params.kd
    .uniform_work_group_size: 1
    .uses_dynamic_stack: false
    .vgpr_count:     256
    .vgpr_spill_count: 0
    .wavefront_size: 64
